# v37 + the four norm loops: loop-invariant gain quads hoisted out (each was a mid-row load followed at once by vmcnt(0), which also waited for the store just issued)
# speedup vs baseline: 1.0092x; 1.0041x over previous
; __device__ __forceinline__ float wave_sum(float v) {
; #pragma unroll
;     for (int o = 1; o < 64; o <<= 1) v += __shfl_xor(v, o);
;     return v;
; }
; __global__ void __launch_bounds__(512, 2) mega_fwd(const Args a) {
;     ...
;     for (int m = gw; m < T; m += NGW) norm_row(xrow(p, m), nullptr, p.in[2], XN + (size_t)m * DM, nullptr, lane);
.LBB0_69:
	s_or_b64 exec, exec, s[14:15]
	s_cmp_lt_i32 s34, 0xc000
	v_readlane_b32 s16, v237, 5
	s_cselect_b64 s[52:53], -1, 0
	s_cmp_gt_i32 s34, 0xbfff
	v_mbcnt_lo_u32_b32 v210, -1, 0
	v_lshlrev_b32_e32 v164, 4, v166
	v_lshlrev_b32_e32 v128, 3, v166
	v_readlane_b32 s17, v237, 6
	v_readlane_b32 s18, v237, 7
	v_readlane_b32 s19, v237, 8
	v_readlane_b32 s20, v237, 9
	v_readlane_b32 s21, v237, 10
	v_readlane_b32 s22, v237, 11
	v_readlane_b32 s23, v237, 12
	v_readlane_b32 s24, v237, 13
	v_readlane_b32 s25, v237, 14
	v_readlane_b32 s26, v237, 15
	v_readlane_b32 s27, v237, 16
	v_readlane_b32 s28, v237, 17
	v_readlane_b32 s29, v237, 18
	v_readlane_b32 s30, v237, 19
	v_readlane_b32 s31, v237, 20
	s_cbranch_scc1 .LBB0_72
	v_mbcnt_hi_u32_b32 v2, -1, v210
	v_and_b32_e32 v1, 64, v2
	v_add_u32_e32 v3, 64, v1
	v_xor_b32_e32 v1, 1, v2
	v_cmp_lt_i32_e32 vcc, v1, v3
	v_xor_b32_e32 v4, 2, v2
	s_ashr_i32 s35, s34, 31
	v_cndmask_b32_e32 v1, v2, v1, vcc
	v_cmp_lt_i32_e32 vcc, v4, v3
	s_lshl_b64 s[0:1], s[34:35], 11
	v_mov_b32_e32 v165, 0
	v_cndmask_b32_e32 v4, v2, v4, vcc
	v_lshlrev_b32_e32 v6, 2, v4
	v_xor_b32_e32 v4, 4, v2
	v_cmp_lt_i32_e32 vcc, v4, v3
	s_add_u32 s0, s50, s0
	v_mov_b32_e32 v129, v165
	v_cndmask_b32_e32 v4, v2, v4, vcc
	v_lshlrev_b32_e32 v7, 2, v4
	v_xor_b32_e32 v4, 8, v2
	v_cmp_lt_i32_e32 vcc, v4, v3
	s_addc_u32 s1, s51, s1
	s_ashr_i32 s89, s88, 31
	v_cndmask_b32_e32 v4, v2, v4, vcc
	v_lshlrev_b32_e32 v8, 2, v4
	v_xor_b32_e32 v4, 16, v2
	v_cmp_lt_i32_e32 vcc, v4, v3
	v_lshlrev_b32_e32 v1, 2, v1
	s_lshl_b64 s[4:5], s[88:89], 11
	v_cndmask_b32_e32 v4, v2, v4, vcc
	v_lshlrev_b32_e32 v9, 2, v4
	v_xor_b32_e32 v4, 32, v2
	v_cmp_lt_i32_e32 vcc, v4, v3
	v_lshlrev_b32_e32 v11, 4, v166
	v_mov_b32_e32 v12, 0x358637bd
	v_cndmask_b32_e32 v2, v2, v4, vcc
	v_lshl_add_u64 v[4:5], s[0:1], 0, v[128:129]
	s_mov_b64 s[0:1], 0x19800000
	v_lshlrev_b32_e32 v10, 2, v2
	v_lshl_add_u64 v[2:3], s[20:21], 0, v[164:165]
	v_lshl_add_u64 v[4:5], v[4:5], 0, s[0:1]
	s_mov_b32 s3, 0xf800000
	v_mov_b32_e32 v13, 0x260
	s_mov_b64 s[6:7], s[34:35]
	global_load_dwordx4 v[192:195], v[2:3], off offset:1024
	global_load_dwordx4 v[196:199], v[2:3], off offset:2048
	global_load_dwordx4 v[200:203], v[2:3], off offset:3072
	s_waitcnt vmcnt(0)
; __device__ __forceinline__ float bflo(unsigned w) { return __uint_as_float(w << 16); }
; __device__ __forceinline__ float bfhi(unsigned w) { return __uint_as_float(w & 0xffff0000u); }
; __device__ __forceinline__ unsigned pkbf(float lo, float hi) { return pg8::cvt_pk_bf16(lo, hi); }
; __device__ __forceinline__ void norm_row(const float* src, const bf16_t* add, const float* gain, bf16_t* ob, float* of, int lane) {
;     f32x4 v[4]; float s = 0.f;
; #pragma unroll
;     for (int j = 0; j < 4; ++j) { v[j] = *((const f32x4*)src + lane + 64 * j);
;         if (add) { const u32x2 d = *((const u32x2*)add + lane + 64 * j); v[j][0] += bflo(d.x); v[j][1] += bfhi(d.x); v[j][2] += bflo(d.y); v[j][3] += bfhi(d.y); }
;         s += (v[j][0] * v[j][0] + v[j][1] * v[j][1]) + (v[j][2] * v[j][2] + v[j][3] * v[j][3]); }
;     const float rstd = 1.0f / sqrtf(wave_sum(s) * (1.f / DM) + NORM_EPS);
; #pragma unroll
;     for (int j = 0; j < 4; ++j) { const f32x4 g = *((const f32x4*)gain + lane + 64 * j); const f32x4 o = v[j] * rstd * g;
;         if (ob) { u32x2 w; w.x = pkbf(o[0], o[1]); w.y = pkbf(o[2], o[3]); *((u32x2*)ob + lane + 64 * j) = w; }
;         else *((f32x4*)of + lane + 64 * j) = o; }
; }
.LBB0_71:
	s_add_i32 s0, s6, 0xffff8000
	s_cmp_lt_i32 s6, 0x8000
	s_cselect_b32 s1, s7, 0
	s_cselect_b32 s0, s6, s0
	s_cselect_b32 s8, s17, s19
	s_cselect_b32 s9, s16, s18
	s_lshl_b64 s[0:1], s[0:1], 12
	s_add_u32 s0, s9, s0
	s_addc_u32 s1, s8, s1
	global_load_dwordx4 v[14:17], v11, s[0:1] nt
	global_load_dwordx4 v[18:21], v11, s[0:1] offset:1024 nt
	global_load_dwordx4 v[22:25], v11, s[0:1] offset:2048 nt
	global_load_dwordx4 v[26:29], v11, s[0:1] offset:3072 nt
	global_load_dwordx4 v[30:33], v[2:3], off
	s_add_u32 s6, s6, s88
	s_addc_u32 s7, s7, s89
	s_cmp_gt_i32 s6, 0xbfff
	s_waitcnt vmcnt(4)
	v_pk_mul_f32 v[34:35], v[16:17], v[16:17]
	v_pk_mul_f32 v[36:37], v[14:15], v[14:15]
	s_waitcnt vmcnt(3)
	v_pk_mul_f32 v[38:39], v[20:21], v[20:21]
	v_pk_mul_f32 v[40:41], v[18:19], v[18:19]
	v_pk_mov_b32 v[46:47], v[36:37], v[34:35] op_sel:[1,0]
	v_mov_b32_e32 v37, v35
	v_pk_mov_b32 v[34:35], v[40:41], v[38:39] op_sel:[1,0]
	v_mov_b32_e32 v41, v39
	s_waitcnt vmcnt(1)
	v_mul_f32_e32 v45, v26, v26
	v_mul_f32_e32 v42, v23, v23
	v_mul_f32_e32 v44, v25, v25
	v_pk_add_f32 v[36:37], v[46:47], v[36:37]
	v_pk_add_f32 v[34:35], v[34:35], v[40:41]
	v_mul_f32_e32 v48, v27, v27
	v_mul_f32_e32 v49, v28, v28
	v_mul_f32_e32 v50, v29, v29
	v_pk_fma_f32 v[38:39], v[22:23], v[22:23], v[42:43] op_sel_hi:[1,1,0]
	v_pk_fma_f32 v[42:43], v[24:25], v[24:25], v[44:45] op_sel_hi:[1,1,0]
	v_pk_add_f32 v[36:37], v[36:37], v[36:37] op_sel:[0,1] op_sel_hi:[1,0]
	v_pk_add_f32 v[34:35], v[34:35], v[34:35] op_sel:[0,1] op_sel_hi:[1,0]
	v_mov_b32_e32 v39, v49
	v_mov_b32_e32 v43, v50
	v_mov_b32_e32 v37, v45
	v_mov_b32_e32 v35, v48
	v_pk_add_f32 v[38:39], v[38:39], v[42:43]
	v_pk_add_f32 v[34:35], v[36:37], v[34:35]
	s_nop 0
	v_pk_add_f32 v[34:35], v[34:35], v[38:39]
	s_nop 0
	v_add_f32_e32 v34, v34, v35
	s_nop 1
	v_add_f32_dpp v34, v34, v34 quad_perm:[1,0,3,2] row_mask:0xf bank_mask:0xf bound_ctrl:1
	s_nop 1
	v_add_f32_dpp v34, v34, v34 quad_perm:[2,3,0,1] row_mask:0xf bank_mask:0xf bound_ctrl:1
	s_nop 1
	v_add_f32_dpp v34, v34, v34 row_half_mirror row_mask:0xf bank_mask:0xf bound_ctrl:1
	s_nop 1
	v_add_f32_dpp v34, v34, v34 row_mirror row_mask:0xf bank_mask:0xf bound_ctrl:1
	s_nop 0
	v_readlane_b32 s98, v34, 0
	v_readlane_b32 s99, v34, 16
	v_readlane_b32 s100, v34, 32
	v_readlane_b32 s101, v34, 48
	v_mov_b32_e32 v34, s98
	v_add_f32_e32 v34, s99, v34
	v_mov_b32_e32 v35, s100
	v_add_f32_e32 v35, s101, v35
	v_add_f32_e32 v34, v34, v35
	v_fmamk_f32 v34, v34, 0x3a800000, v12
	v_mul_f32_e32 v35, 0x4f800000, v34
	v_cmp_gt_f32_e32 vcc, s3, v34
	s_nop 1
	v_cndmask_b32_e32 v34, v34, v35, vcc
	v_sqrt_f32_e32 v35, v34
	s_nop 0
	v_add_u32_e32 v36, -1, v35
	v_add_u32_e32 v37, 1, v35
	v_fma_f32 v38, -v36, v35, v34
	v_fma_f32 v39, -v37, v35, v34
	v_cmp_ge_f32_e64 s[0:1], 0, v38
	s_nop 1
	v_cndmask_b32_e64 v35, v35, v36, s[0:1]
	v_cmp_lt_f32_e64 s[0:1], 0, v39
	s_nop 1
	v_cndmask_b32_e64 v35, v35, v37, s[0:1]
	v_mul_f32_e32 v36, 0x37800000, v35
	v_cndmask_b32_e32 v35, v35, v36, vcc
	v_cmp_class_f32_e32 vcc, v34, v13
	s_nop 1
	v_cndmask_b32_e32 v34, v35, v34, vcc
	v_div_scale_f32 v35, s[0:1], v34, v34, 1.0
	v_rcp_f32_e32 v37, v35
	v_div_scale_f32 v36, vcc, 1.0, v34, 1.0
	v_fma_f32 v38, -v35, v37, 1.0
	v_fmac_f32_e32 v37, v38, v37
	v_mul_f32_e32 v38, v36, v37
	v_fma_f32 v39, -v35, v38, v36
	v_fmac_f32_e32 v38, v39, v37
	v_fma_f32 v35, -v35, v38, v36
	v_div_fmas_f32 v35, v35, v37, v38
	v_div_fixup_f32 v34, v35, v34, 1.0
	v_pk_mul_f32 v[14:15], v[14:15], v[34:35] op_sel_hi:[1,0]
	v_pk_mul_f32 v[16:17], v[16:17], v[34:35] op_sel_hi:[1,0]
	s_waitcnt vmcnt(0)
	v_pk_mul_f32 v[14:15], v[30:31], v[14:15]
	v_pk_mul_f32 v[16:17], v[32:33], v[16:17]
	v_cvt_pk_bf16_f32 v14, v14, v15
	v_pk_mul_f32 v[18:19], v[18:19], v[34:35] op_sel_hi:[1,0]
	v_cvt_pk_bf16_f32 v15, v16, v17
	global_store_dwordx2 v[4:5], v[14:15], off
	s_nop 1
	v_mov_b64_e32 v[14:15], v[192:193]
	v_mov_b64_e32 v[16:17], v[194:195]
	v_pk_mul_f32 v[20:21], v[20:21], v[34:35] op_sel_hi:[1,0]
	s_nop 0
	v_pk_mul_f32 v[14:15], v[14:15], v[18:19]
	v_pk_mul_f32 v[16:17], v[16:17], v[20:21]
	v_cvt_pk_bf16_f32 v14, v14, v15
	v_pk_mul_f32 v[18:19], v[22:23], v[34:35] op_sel_hi:[1,0]
	v_cvt_pk_bf16_f32 v15, v16, v17
	global_store_dwordx2 v[4:5], v[14:15], off offset:512
	s_nop 1
	v_mov_b64_e32 v[14:15], v[196:197]
	v_mov_b64_e32 v[16:17], v[198:199]
	v_pk_mul_f32 v[20:21], v[24:25], v[34:35] op_sel_hi:[1,0]
	s_nop 0
	v_pk_mul_f32 v[14:15], v[14:15], v[18:19]
	v_pk_mul_f32 v[16:17], v[16:17], v[20:21]
	v_cvt_pk_bf16_f32 v14, v14, v15
	v_pk_mul_f32 v[18:19], v[26:27], v[34:35] op_sel_hi:[1,0]
	v_cvt_pk_bf16_f32 v15, v16, v17
	global_store_dwordx2 v[4:5], v[14:15], off offset:1024
	s_nop 1
	v_mov_b64_e32 v[14:15], v[200:201]
	v_mov_b64_e32 v[16:17], v[202:203]
	v_pk_mul_f32 v[20:21], v[28:29], v[34:35] op_sel_hi:[1,0]
	s_nop 0
	v_pk_mul_f32 v[14:15], v[18:19], v[14:15]
	v_pk_mul_f32 v[16:17], v[20:21], v[16:17]
	v_cvt_pk_bf16_f32 v14, v14, v15
	s_nop 0
	v_cvt_pk_bf16_f32 v15, v16, v17
	global_store_dwordx2 v[4:5], v[14:15], off offset:1536
	v_lshl_add_u64 v[4:5], v[4:5], 0, s[4:5]
	s_cbranch_scc0 .LBB0_71

; __device__ __forceinline__ float bflo(unsigned w) { return __uint_as_float(w << 16); }
; __device__ __forceinline__ float bfhi(unsigned w) { return __uint_as_float(w & 0xffff0000u); }
; __device__ __forceinline__ unsigned pkbf(float lo, float hi) { return pg8::cvt_pk_bf16(lo, hi); }
; __device__ __forceinline__ void norm_row(const float* src, const bf16_t* add, const float* gain, bf16_t* ob, float* of, int lane) {
;     f32x4 v[4]; float s = 0.f;
; #pragma unroll
;     for (int j = 0; j < 4; ++j) { v[j] = *((const f32x4*)src + lane + 64 * j);
;         if (add) { const u32x2 d = *((const u32x2*)add + lane + 64 * j); v[j][0] += bflo(d.x); v[j][1] += bfhi(d.x); v[j][2] += bflo(d.y); v[j][3] += bfhi(d.y); }
;         s += (v[j][0] * v[j][0] + v[j][1] * v[j][1]) + (v[j][2] * v[j][2] + v[j][3] * v[j][3]); }
;     const float rstd = 1.0f / sqrtf(wave_sum(s) * (1.f / DM) + NORM_EPS);
; #pragma unroll
;     for (int j = 0; j < 4; ++j) { const f32x4 g = *((const f32x4*)gain + lane + 64 * j); const f32x4 o = v[j] * rstd * g;
;         if (ob) { u32x2 w; w.x = pkbf(o[0], o[1]); w.y = pkbf(o[2], o[3]); *((u32x2*)ob + lane + 64 * j) = w; }
;         else *((f32x4*)of + lane + 64 * j) = o; }
; }
; __global__ void __launch_bounds__(512, 2) mega_fwd(const Args a) {
;     ...
;     for (int m = gw; m < T; m += NGW) norm_row(xrow(p, m), D1 + (size_t)m * DM, p.in[6], XN + (size_t)m * DM, nullptr, lane);
.LBB0_282:
	s_or_b64 exec, exec, s[0:1]
	s_waitcnt lgkmcnt(0)
	v_cndmask_b32_e64 v0, 0, 1, s[52:53]
	v_cmp_ne_u32_e64 s[0:1], 1, v0
	s_andn2_b64 vcc, exec, s[52:53]
	s_nop 0
	v_writelane_b32 v237, s0, 63
	s_barrier
	v_readlane_b32 s52, v237, 5
	v_readlane_b32 s53, v237, 6
	v_readlane_b32 s54, v237, 7
	v_readlane_b32 s55, v237, 8
	v_readlane_b32 s64, v237, 17
	v_readlane_b32 s65, v237, 18
	v_writelane_b32 v236, s1, 0
	v_readlane_b32 s56, v237, 9
	v_readlane_b32 s57, v237, 10
	v_readlane_b32 s58, v237, 11
	v_readlane_b32 s59, v237, 12
	v_readlane_b32 s60, v237, 13
	v_readlane_b32 s61, v237, 14
	v_readlane_b32 s62, v237, 15
	v_readlane_b32 s63, v237, 16
	v_readlane_b32 s66, v237, 19
	v_readlane_b32 s67, v237, 20
	s_cbranch_vccnz .LBB0_285
	v_mbcnt_hi_u32_b32 v0, -1, v210
	v_and_b32_e32 v1, 64, v0
	v_add_u32_e32 v1, 64, v1
	v_xor_b32_e32 v2, 1, v0
	v_cmp_lt_i32_e32 vcc, v2, v1
	s_ashr_i32 s35, s34, 31
	s_lshl_b64 s[0:1], s[34:35], 11
	v_cndmask_b32_e32 v2, v0, v2, vcc
	v_lshlrev_b32_e32 v4, 2, v2
	v_xor_b32_e32 v2, 2, v0
	v_cmp_lt_i32_e32 vcc, v2, v1
	v_mov_b32_e32 v165, 0
	s_add_u32 s0, s50, s0
	v_cndmask_b32_e32 v2, v0, v2, vcc
	v_lshlrev_b32_e32 v5, 2, v2
	v_xor_b32_e32 v2, 4, v0
	v_cmp_lt_i32_e32 vcc, v2, v1
	v_mov_b32_e32 v129, v165
	s_addc_u32 s1, s51, s1
	v_cndmask_b32_e32 v2, v0, v2, vcc
	v_lshlrev_b32_e32 v6, 2, v2
	v_xor_b32_e32 v2, 8, v0
	v_cmp_lt_i32_e32 vcc, v2, v1
	s_mov_b64 s[16:17], s[52:53]
	s_mov_b64 s[28:29], s[64:65]
	v_cndmask_b32_e32 v2, v0, v2, vcc
	v_lshlrev_b32_e32 v7, 2, v2
	v_xor_b32_e32 v2, 16, v0
	v_cmp_lt_i32_e32 vcc, v2, v1
	s_ashr_i32 s89, s88, 31
	s_mov_b64 s[18:19], s[54:55]
	v_cndmask_b32_e32 v2, v0, v2, vcc
	v_lshlrev_b32_e32 v8, 2, v2
	v_xor_b32_e32 v2, 32, v0
	v_cmp_lt_i32_e32 vcc, v2, v1
	s_lshl_b64 s[4:5], s[88:89], 11
	v_lshlrev_b32_e32 v10, 4, v166
	v_cndmask_b32_e32 v0, v0, v2, vcc
	v_lshl_add_u64 v[2:3], s[0:1], 0, v[128:129]
	s_mov_b64 s[0:1], 0x19800000
	v_lshlrev_b32_e32 v9, 2, v0
	v_lshl_add_u64 v[0:1], s[28:29], 0, v[164:165]
	v_lshl_add_u64 v[2:3], v[2:3], 0, s[0:1]
	s_mov_b32 s3, 0xe9800000
	s_mov_b32 s8, 0xe9801000
	v_mov_b32_e32 v11, 0x358637bd
	s_mov_b32 s9, 0xf800000
	v_mov_b32_e32 v12, 0x260
	s_mov_b64 s[6:7], s[34:35]
	global_load_dwordx4 v[192:195], v[0:1], off offset:1024
	global_load_dwordx4 v[196:199], v[0:1], off offset:2048
	global_load_dwordx4 v[200:203], v[0:1], off offset:3072
	s_waitcnt vmcnt(0)
; __device__ __forceinline__ float bflo(unsigned w) { return __uint_as_float(w << 16); }
; __device__ __forceinline__ float bfhi(unsigned w) { return __uint_as_float(w & 0xffff0000u); }
; __device__ __forceinline__ unsigned pkbf(float lo, float hi) { return pg8::cvt_pk_bf16(lo, hi); }
; __device__ __forceinline__ void norm_row(const float* src, const bf16_t* add, const float* gain, bf16_t* ob, float* of, int lane) {
;     f32x4 v[4]; float s = 0.f;
; #pragma unroll
;     for (int j = 0; j < 4; ++j) { v[j] = *((const f32x4*)src + lane + 64 * j);
;         if (add) { const u32x2 d = *((const u32x2*)add + lane + 64 * j); v[j][0] += bflo(d.x); v[j][1] += bfhi(d.x); v[j][2] += bflo(d.y); v[j][3] += bfhi(d.y); }
;         s += (v[j][0] * v[j][0] + v[j][1] * v[j][1]) + (v[j][2] * v[j][2] + v[j][3] * v[j][3]); }
;     const float rstd = 1.0f / sqrtf(wave_sum(s) * (1.f / DM) + NORM_EPS);
; #pragma unroll
;     for (int j = 0; j < 4; ++j) { const f32x4 g = *((const f32x4*)gain + lane + 64 * j); const f32x4 o = v[j] * rstd * g;
;         if (ob) { u32x2 w; w.x = pkbf(o[0], o[1]); w.y = pkbf(o[2], o[3]); *((u32x2*)ob + lane + 64 * j) = w; }
;         else *((f32x4*)of + lane + 64 * j) = o; }
; }
; __global__ void __launch_bounds__(512, 2) mega_fwd(const Args a) {
;     ...
;     for (int m = gw; m < T; m += NGW) norm_row(xrow(p, m), D1 + (size_t)m * DM, p.in[6], XN + (size_t)m * DM, nullptr, lane);
.LBB0_284:
	s_add_i32 s12, s6, 0xffff8000
	v_add_co_u32_e64 v16, s[0:1], s8, v2
	v_add_co_u32_e32 v14, vcc, s3, v2
	s_nop 0
	v_addc_co_u32_e64 v17, s[0:1], -1, v3, s[0:1]
	s_cmp_lt_i32 s6, 0x8000
	v_addc_co_u32_e32 v15, vcc, -1, v3, vcc
	s_cselect_b32 s1, s7, 0
	s_cselect_b32 s0, s6, s12
	global_load_dwordx2 v[34:35], v[14:15], off nt
	global_load_dwordx2 v[36:37], v[16:17], off offset:-3584 nt
	s_cselect_b32 s12, s17, s19
	s_cselect_b32 s13, s16, s18
	s_lshl_b64 s[0:1], s[0:1], 12
	global_load_dwordx2 v[38:39], v[16:17], off offset:-3072 nt
	global_load_dwordx2 v[40:41], v[16:17], off offset:-2560 nt
	s_add_u32 s0, s13, s0
	s_addc_u32 s1, s12, s1
	global_load_dwordx4 v[14:17], v10, s[0:1] nt
	global_load_dwordx4 v[18:21], v10, s[0:1] offset:1024 nt
	global_load_dwordx4 v[22:25], v10, s[0:1] offset:2048 nt
	global_load_dwordx4 v[26:29], v10, s[0:1] offset:3072 nt
	global_load_dwordx4 v[30:33], v[0:1], off
	s_add_u32 s6, s6, s88
	s_addc_u32 s7, s7, s89
	s_cmp_gt_i32 s6, 0xbfff
	s_waitcnt vmcnt(8)
	v_lshlrev_b32_e32 v42, 16, v34
	v_and_b32_e32 v43, 0xffff0000, v34
	v_lshlrev_b32_e32 v34, 16, v35
	v_and_b32_e32 v35, 0xffff0000, v35
	s_waitcnt vmcnt(7)
	v_lshlrev_b32_e32 v44, 16, v36
	v_and_b32_e32 v45, 0xffff0000, v36
	v_lshlrev_b32_e32 v36, 16, v37
	v_and_b32_e32 v37, 0xffff0000, v37
	s_waitcnt vmcnt(5)
	v_lshlrev_b32_e32 v48, 16, v40
	v_and_b32_e32 v49, 0xffff0000, v40
	v_lshlrev_b32_e32 v40, 16, v41
	v_and_b32_e32 v41, 0xffff0000, v41
	s_waitcnt vmcnt(4)
	v_pk_add_f32 v[14:15], v[14:15], v[42:43]
	v_pk_add_f32 v[16:17], v[16:17], v[34:35]
	s_waitcnt vmcnt(3)
	v_pk_add_f32 v[18:19], v[18:19], v[44:45]
	v_pk_add_f32 v[20:21], v[20:21], v[36:37]
	v_lshlrev_b32_e32 v46, 16, v38
	v_and_b32_e32 v47, 0xffff0000, v38
	v_lshlrev_b32_e32 v38, 16, v39
	v_and_b32_e32 v39, 0xffff0000, v39
	s_waitcnt vmcnt(1)
	v_pk_add_f32 v[28:29], v[28:29], v[40:41]
	v_mov_b32_e32 v36, v15
	v_mov_b32_e32 v37, v17
	v_mov_b32_e32 v40, v19
	v_mov_b32_e32 v41, v21
	v_pk_add_f32 v[22:23], v[22:23], v[46:47]
	v_pk_add_f32 v[24:25], v[24:25], v[38:39]
	v_mov_b32_e32 v34, v14
	v_mov_b32_e32 v35, v16
	v_mov_b32_e32 v38, v18
	v_mov_b32_e32 v39, v20
	v_pk_mul_f32 v[36:37], v[36:37], v[36:37]
	v_pk_mul_f32 v[40:41], v[40:41], v[40:41]
	v_pk_add_f32 v[26:27], v[26:27], v[48:49]
	v_mul_f32_e32 v42, v23, v23
	v_mul_f32_e32 v44, v25, v25
	v_pk_fma_f32 v[34:35], v[34:35], v[34:35], v[36:37]
	v_pk_fma_f32 v[36:37], v[38:39], v[38:39], v[40:41]
	v_pk_mul_f32 v[46:47], v[26:27], v[26:27]
	v_pk_mul_f32 v[48:49], v[28:29], v[28:29]
	v_pk_fma_f32 v[42:43], v[22:23], v[22:23], v[42:43] op_sel_hi:[1,1,0]
	v_pk_fma_f32 v[44:45], v[24:25], v[24:25], v[44:45] op_sel_hi:[1,1,0]
	v_pk_add_f32 v[34:35], v[34:35], v[34:35] op_sel:[0,1] op_sel_hi:[1,0]
	v_pk_add_f32 v[36:37], v[36:37], v[36:37] op_sel:[0,1] op_sel_hi:[1,0]
	v_mov_b32_e32 v43, v48
	v_mov_b32_e32 v45, v49
	v_mov_b32_e32 v35, v46
	v_mov_b32_e32 v37, v47
	v_pk_add_f32 v[38:39], v[42:43], v[44:45]
	v_pk_add_f32 v[34:35], v[34:35], v[36:37]
	s_nop 0
	v_pk_add_f32 v[34:35], v[34:35], v[38:39]
	s_nop 0
	v_add_f32_e32 v13, v34, v35
	s_nop 1
	v_add_f32_dpp v13, v13, v13 quad_perm:[1,0,3,2] row_mask:0xf bank_mask:0xf bound_ctrl:1
	s_nop 1
	v_add_f32_dpp v13, v13, v13 quad_perm:[2,3,0,1] row_mask:0xf bank_mask:0xf bound_ctrl:1
	s_nop 1
	v_add_f32_dpp v13, v13, v13 row_half_mirror row_mask:0xf bank_mask:0xf bound_ctrl:1
	s_nop 1
	v_add_f32_dpp v13, v13, v13 row_mirror row_mask:0xf bank_mask:0xf bound_ctrl:1
	s_nop 0
	v_readlane_b32 s98, v13, 0
	v_readlane_b32 s99, v13, 16
	v_readlane_b32 s100, v13, 32
	v_readlane_b32 s101, v13, 48
	v_mov_b32_e32 v13, s98
	v_add_f32_e32 v13, s99, v13
	v_mov_b32_e32 v34, s100
	v_add_f32_e32 v34, s101, v34
	v_add_f32_e32 v13, v13, v34
	v_fmamk_f32 v13, v13, 0x3a800000, v11
	v_mul_f32_e32 v34, 0x4f800000, v13
	v_cmp_gt_f32_e32 vcc, s9, v13
	s_nop 1
	v_cndmask_b32_e32 v13, v13, v34, vcc
	v_sqrt_f32_e32 v34, v13
	s_nop 0
	v_add_u32_e32 v35, -1, v34
	v_add_u32_e32 v36, 1, v34
	v_fma_f32 v37, -v35, v34, v13
	v_fma_f32 v38, -v36, v34, v13
	v_cmp_ge_f32_e64 s[0:1], 0, v37
	s_nop 1
	v_cndmask_b32_e64 v34, v34, v35, s[0:1]
	v_cmp_lt_f32_e64 s[0:1], 0, v38
	s_nop 1
	v_cndmask_b32_e64 v34, v34, v36, s[0:1]
	v_mul_f32_e32 v35, 0x37800000, v34
	v_cndmask_b32_e32 v34, v34, v35, vcc
	v_cmp_class_f32_e32 vcc, v13, v12
	s_nop 1
	v_cndmask_b32_e32 v13, v34, v13, vcc
	v_div_scale_f32 v34, s[0:1], v13, v13, 1.0
	v_rcp_f32_e32 v36, v34
	v_div_scale_f32 v35, vcc, 1.0, v13, 1.0
	v_fma_f32 v37, -v34, v36, 1.0
	v_fmac_f32_e32 v36, v37, v36
	v_mul_f32_e32 v37, v35, v36
	v_fma_f32 v38, -v34, v37, v35
	v_fmac_f32_e32 v37, v38, v36
	v_fma_f32 v34, -v34, v37, v35
	v_div_fmas_f32 v34, v34, v36, v37
	v_div_fixup_f32 v34, v34, v13, 1.0
	v_pk_mul_f32 v[14:15], v[14:15], v[34:35] op_sel_hi:[1,0]
	v_pk_mul_f32 v[16:17], v[16:17], v[34:35] op_sel_hi:[1,0]
	s_waitcnt vmcnt(0)
	v_pk_mul_f32 v[14:15], v[30:31], v[14:15]
	v_pk_mul_f32 v[16:17], v[32:33], v[16:17]
	v_cvt_pk_bf16_f32 v14, v14, v15
	v_pk_mul_f32 v[18:19], v[18:19], v[34:35] op_sel_hi:[1,0]
	v_cvt_pk_bf16_f32 v15, v16, v17
	global_store_dwordx2 v[2:3], v[14:15], off
	s_nop 1
	v_mov_b64_e32 v[14:15], v[192:193]
	v_mov_b64_e32 v[16:17], v[194:195]
	v_pk_mul_f32 v[20:21], v[20:21], v[34:35] op_sel_hi:[1,0]
	s_nop 0
	v_pk_mul_f32 v[14:15], v[14:15], v[18:19]
	v_pk_mul_f32 v[16:17], v[16:17], v[20:21]
	v_cvt_pk_bf16_f32 v14, v14, v15
	v_pk_mul_f32 v[18:19], v[22:23], v[34:35] op_sel_hi:[1,0]
	v_cvt_pk_bf16_f32 v15, v16, v17
	global_store_dwordx2 v[2:3], v[14:15], off offset:512
	s_nop 1
	v_mov_b64_e32 v[14:15], v[196:197]
	v_mov_b64_e32 v[16:17], v[198:199]
	v_pk_mul_f32 v[20:21], v[24:25], v[34:35] op_sel_hi:[1,0]
	s_nop 0
	v_pk_mul_f32 v[14:15], v[14:15], v[18:19]
	v_pk_mul_f32 v[16:17], v[16:17], v[20:21]
	v_cvt_pk_bf16_f32 v14, v14, v15
	v_pk_mul_f32 v[18:19], v[26:27], v[34:35] op_sel_hi:[1,0]
	v_cvt_pk_bf16_f32 v15, v16, v17
	global_store_dwordx2 v[2:3], v[14:15], off offset:1024
	s_nop 1
	v_mov_b64_e32 v[14:15], v[200:201]
	v_mov_b64_e32 v[16:17], v[202:203]
	v_pk_mul_f32 v[20:21], v[28:29], v[34:35] op_sel_hi:[1,0]
	s_nop 0
	v_pk_mul_f32 v[14:15], v[18:19], v[14:15]
	v_pk_mul_f32 v[16:17], v[20:21], v[16:17]
	v_cvt_pk_bf16_f32 v14, v14, v15
	s_nop 0
	v_cvt_pk_bf16_f32 v15, v16, v17
	global_store_dwordx2 v[2:3], v[14:15], off offset:1536
	v_lshl_add_u64 v[2:3], v[2:3], 0, s[4:5]
	s_cbranch_scc0 .LBB0_284

; __device__ __forceinline__ unsigned pkbf(float lo, float hi) { return pg8::cvt_pk_bf16(lo, hi); }
; __device__ __forceinline__ void unpack8bf(const u32x4 w, float* f) { f[0] = bflo(w.x); f[1] = bfhi(w.x); f[2] = bflo(w.y); f[3] = bfhi(w.y); f[4] = bflo(w.z); f[5] = bfhi(w.z); f[6] = bflo(w.w); f[7] = bfhi(w.w); }
; __device__ __forceinline__ void norm_row_bf(const bf16_t* src, const float* gain, bf16_t* ob, float* of, int lane) {
;     float v[16]; float s = 0.f;
;     const u32x4 w0 = *((const u32x4*)src + lane), w1 = *((const u32x4*)src + lane + 64);
;     unpack8bf(w0, v); unpack8bf(w1, v + 8);
; #pragma unroll
;     for (int e = 0; e < 16; ++e) s += v[e] * v[e];
;     const float rstd = 1.0f / sqrtf(wave_sum(s) * (1.f / DM) + NORM_EPS);
; #pragma unroll
;     for (int h = 0; h < 2; ++h) { const float* g = gain + h * 512 + lane * 8; const f32x4 g0 = *(const f32x4*)g, g1 = *(const f32x4*)(g + 4);
;         float o[8];
; #pragma unroll
;         for (int e = 0; e < 4; ++e) { o[e] = v[h * 8 + e] * rstd * g0[e]; o[4 + e] = v[h * 8 + 4 + e] * rstd * g1[e]; }
;         if (ob) { u32x4 w; w.x = pkbf(o[0], o[1]); w.y = pkbf(o[2], o[3]); w.z = pkbf(o[4], o[5]); w.w = pkbf(o[6], o[7]); *((u32x4*)ob + lane + 64 * h) = w; }
;         else { const f32x4 a = {o[0], o[1], o[2], o[3]}, b = {o[4], o[5], o[6], o[7]}; *(f32x4*)(of + h * 512 + lane * 8) = a; *(f32x4*)(of + h * 512 + lane * 8 + 4) = b; } }
; }
; __global__ void __launch_bounds__(512, 2) mega_fwd(const Args a) {
;     ...
;     for (int m = gw; m < T; m += NGW) norm_row_bf(D1 + (size_t)m * DM, p.in[25], XN + (size_t)m * DM, nullptr, lane);
.LBB0_1300:
	s_or_b64 exec, exec, s[0:1]
	v_readlane_b32 s0, v237, 63
	v_readlane_b32 s1, v236, 0
	s_and_b64 vcc, exec, s[0:1]
	s_waitcnt lgkmcnt(0)
	s_barrier
	s_cbranch_vccnz .LBB0_1303
	v_mbcnt_hi_u32_b32 v0, -1, v210
	v_and_b32_e32 v1, 64, v0
	v_add_u32_e32 v1, 64, v1
	v_xor_b32_e32 v2, 1, v0
	v_cmp_lt_i32_e32 vcc, v2, v1
	s_ashr_i32 s35, s34, 31
	s_lshl_b64 s[0:1], s[34:35], 11
	v_cndmask_b32_e32 v2, v0, v2, vcc
	v_lshlrev_b32_e32 v4, 2, v2
	v_xor_b32_e32 v2, 2, v0
	v_cmp_lt_i32_e32 vcc, v2, v1
	v_mov_b32_e32 v129, 0
	s_add_u32 s0, s50, s0
	v_cndmask_b32_e32 v2, v0, v2, vcc
	v_lshlrev_b32_e32 v5, 2, v2
	v_xor_b32_e32 v2, 4, v0
	v_cmp_lt_i32_e32 vcc, v2, v1
	v_mov_b32_e32 v165, v129
	s_addc_u32 s1, s51, s1
	v_cndmask_b32_e32 v2, v0, v2, vcc
	v_lshlrev_b32_e32 v6, 2, v2
	v_xor_b32_e32 v2, 8, v0
	v_cmp_lt_i32_e32 vcc, v2, v1
	s_ashr_i32 s89, s88, 31
	s_lshl_b64 s[4:5], s[88:89], 11
	v_cndmask_b32_e32 v2, v0, v2, vcc
	v_lshlrev_b32_e32 v7, 2, v2
	v_xor_b32_e32 v2, 16, v0
	v_cmp_lt_i32_e32 vcc, v2, v1
	v_mov_b32_e32 v10, 0x358637bd
	s_mov_b32 s3, 0xf800000
	v_cndmask_b32_e32 v2, v0, v2, vcc
	v_lshlrev_b32_e32 v8, 2, v2
	v_xor_b32_e32 v2, 32, v0
	v_cmp_lt_i32_e32 vcc, v2, v1
	v_mov_b32_e32 v11, 0x260
	s_mov_b32 s6, s34
	v_cndmask_b32_e32 v0, v0, v2, vcc
	v_lshl_add_u64 v[2:3], s[0:1], 0, v[164:165]
	s_mov_b64 s[0:1], 0x19800000
	v_lshlrev_b32_e32 v9, 2, v0
	v_lshl_add_u64 v[0:1], s[38:39], 0, v[128:129]
	v_lshl_add_u64 v[2:3], v[2:3], 0, s[0:1]
	global_load_dwordx4 v[192:195], v[0:1], off offset:2048
	global_load_dwordx4 v[196:199], v[0:1], off offset:2064
	s_waitcnt vmcnt(0)
.LBB0_1302:
	v_add_co_u32_e32 v12, vcc, 0xe9800000, v2
	s_add_i32 s6, s6, s88
	s_nop 0
	v_addc_co_u32_e32 v13, vcc, -1, v3, vcc
	global_load_dwordx4 v[12:15], v[12:13], off nt
	v_add_co_u32_e32 v28, vcc, 0xe9801000, v2
	s_cmp_gt_i32 s6, 0xbfff
	s_nop 0
	v_addc_co_u32_e32 v29, vcc, -1, v3, vcc
	global_load_dwordx4 v[16:19], v[28:29], off offset:-3072 nt
	global_load_dwordx4 v[20:23], v[0:1], off offset:16
	global_load_dwordx4 v[24:27], v[0:1], off
	s_waitcnt vmcnt(3)
	v_lshlrev_b32_e32 v28, 16, v12
	v_and_b32_e32 v12, 0xffff0000, v12
	v_lshlrev_b32_e32 v29, 16, v13
	v_and_b32_e32 v13, 0xffff0000, v13
	s_waitcnt vmcnt(2)
	v_lshlrev_b32_e32 v32, 16, v16
	v_and_b32_e32 v33, 0xffff0000, v16
	v_mul_f32_e32 v16, v12, v12
	v_fmac_f32_e32 v16, v28, v28
	v_fmac_f32_e32 v16, v29, v29
	v_lshlrev_b32_e32 v30, 16, v14
	v_fmac_f32_e32 v16, v13, v13
	v_and_b32_e32 v14, 0xffff0000, v14
	v_fmac_f32_e32 v16, v30, v30
	v_lshlrev_b32_e32 v31, 16, v15
	v_fmac_f32_e32 v16, v14, v14
	v_and_b32_e32 v15, 0xffff0000, v15
	v_fmac_f32_e32 v16, v31, v31
	v_fmac_f32_e32 v16, v15, v15
	v_fmac_f32_e32 v16, v32, v32
	v_lshlrev_b32_e32 v34, 16, v17
	v_fmac_f32_e32 v16, v33, v33
	v_and_b32_e32 v35, 0xffff0000, v17
	v_fmac_f32_e32 v16, v34, v34
	v_lshlrev_b32_e32 v36, 16, v18
	v_fmac_f32_e32 v16, v35, v35
	v_and_b32_e32 v37, 0xffff0000, v18
	v_fmac_f32_e32 v16, v36, v36
	v_lshlrev_b32_e32 v38, 16, v19
	v_fmac_f32_e32 v16, v37, v37
	v_and_b32_e32 v39, 0xffff0000, v19
	v_fmac_f32_e32 v16, v38, v38
	v_fmac_f32_e32 v16, v39, v39
	s_nop 1
	v_add_f32_dpp v16, v16, v16 quad_perm:[1,0,3,2] row_mask:0xf bank_mask:0xf bound_ctrl:1
	s_nop 1
	v_add_f32_dpp v16, v16, v16 quad_perm:[2,3,0,1] row_mask:0xf bank_mask:0xf bound_ctrl:1
	s_nop 1
	v_add_f32_dpp v16, v16, v16 row_half_mirror row_mask:0xf bank_mask:0xf bound_ctrl:1
	s_nop 1
	v_add_f32_dpp v16, v16, v16 row_mirror row_mask:0xf bank_mask:0xf bound_ctrl:1
	s_nop 0
	v_readlane_b32 s98, v16, 0
	v_readlane_b32 s99, v16, 16
	v_readlane_b32 s100, v16, 32
	v_readlane_b32 s101, v16, 48
	v_mov_b32_e32 v16, s98
	v_add_f32_e32 v16, s99, v16
	v_mov_b32_e32 v17, s100
	v_add_f32_e32 v17, s101, v17
	v_add_f32_e32 v16, v16, v17
	v_fmamk_f32 v16, v16, 0x3a800000, v10
	v_mul_f32_e32 v17, 0x4f800000, v16
	v_cmp_gt_f32_e32 vcc, s3, v16
	s_nop 1
	v_cndmask_b32_e32 v16, v16, v17, vcc
	v_sqrt_f32_e32 v17, v16
	s_nop 0
	v_add_u32_e32 v18, -1, v17
	v_add_u32_e32 v19, 1, v17
	v_fma_f32 v40, -v18, v17, v16
	v_fma_f32 v41, -v19, v17, v16
	v_cmp_ge_f32_e64 s[0:1], 0, v40
	s_nop 1
	v_cndmask_b32_e64 v17, v17, v18, s[0:1]
	v_cmp_lt_f32_e64 s[0:1], 0, v41
	s_nop 1
	v_cndmask_b32_e64 v17, v17, v19, s[0:1]
	v_mul_f32_e32 v18, 0x37800000, v17
	v_cndmask_b32_e32 v17, v17, v18, vcc
	v_cmp_class_f32_e32 vcc, v16, v11
	s_nop 1
	v_cndmask_b32_e32 v16, v17, v16, vcc
	v_div_scale_f32 v17, s[0:1], v16, v16, 1.0
	v_rcp_f32_e32 v18, v17
	v_div_scale_f32 v19, vcc, 1.0, v16, 1.0
	v_fma_f32 v40, -v17, v18, 1.0
	v_fmac_f32_e32 v18, v40, v18
	v_mul_f32_e32 v40, v19, v18
	v_fma_f32 v41, -v17, v40, v19
	v_fmac_f32_e32 v40, v41, v18
	v_fma_f32 v17, -v17, v40, v19
	v_div_fmas_f32 v17, v17, v18, v40
	v_div_fixup_f32 v40, v17, v16, 1.0
	v_mul_f32_e32 v12, v40, v12
	v_mul_f32_e32 v14, v40, v14
	v_mul_f32_e32 v13, v40, v13
	v_mul_f32_e32 v15, v40, v15
	v_mul_f32_e32 v16, v40, v28
	v_mul_f32_e32 v17, v40, v30
	v_mul_f32_e32 v18, v40, v29
	v_mul_f32_e32 v19, v40, v31
	s_waitcnt vmcnt(0)
	v_mul_f32_e32 v12, v25, v12
	v_mul_f32_e32 v14, v21, v14
	v_mul_f32_e32 v13, v27, v13
	v_mul_f32_e32 v15, v23, v15
	v_mul_f32_e32 v16, v24, v16
	v_mul_f32_e32 v17, v20, v17
	v_mul_f32_e32 v18, v26, v18
	v_mul_f32_e32 v19, v22, v19
	v_cvt_pk_bf16_f32 v12, v16, v12
	v_cvt_pk_bf16_f32 v13, v18, v13
	v_cvt_pk_bf16_f32 v14, v17, v14
	v_cvt_pk_bf16_f32 v15, v19, v15
	global_store_dwordx4 v[2:3], v[12:15], off
	s_nop 1
	v_mov_b64_e32 v[12:13], v[192:193]
	v_mov_b64_e32 v[14:15], v[194:195]
	s_nop 0
	s_nop 1
	v_mov_b64_e32 v[16:17], v[196:197]
	v_mov_b64_e32 v[18:19], v[198:199]
	v_mul_f32_e32 v20, v40, v32
	v_mul_f32_e32 v22, v40, v33
	v_mul_f32_e32 v24, v40, v34
	v_mul_f32_e32 v26, v40, v35
	v_mul_f32_e32 v21, v40, v36
	v_mul_f32_e32 v23, v40, v37
	v_mul_f32_e32 v25, v40, v38
	v_mul_f32_e32 v27, v40, v39
	s_nop 0
	v_mul_f32_e32 v12, v12, v20
	v_mul_f32_e32 v13, v13, v22
	v_mul_f32_e32 v14, v14, v24
	v_mul_f32_e32 v15, v15, v26
	s_nop 0
	v_mul_f32_e32 v16, v16, v21
	v_mul_f32_e32 v17, v17, v23
	v_mul_f32_e32 v18, v18, v25
	v_mul_f32_e32 v19, v19, v27
	v_cvt_pk_bf16_f32 v12, v12, v13
	v_cvt_pk_bf16_f32 v13, v14, v15
	v_cvt_pk_bf16_f32 v14, v16, v17
	v_cvt_pk_bf16_f32 v15, v18, v19
	global_store_dwordx4 v[2:3], v[12:15], off offset:1024
	v_lshl_add_u64 v[2:3], v[2:3], 0, s[4:5]
	s_cbranch_scc0 .LBB0_1302

; __device__ __forceinline__ unsigned pkbf(float lo, float hi) { return pg8::cvt_pk_bf16(lo, hi); }
; __device__ __forceinline__ void unpack8bf(const u32x4 w, float* f) { f[0] = bflo(w.x); f[1] = bfhi(w.x); f[2] = bflo(w.y); f[3] = bfhi(w.y); f[4] = bflo(w.z); f[5] = bfhi(w.z); f[6] = bflo(w.w); f[7] = bfhi(w.w); }
; __device__ __forceinline__ void norm_row_bf(const bf16_t* src, const float* gain, bf16_t* ob, float* of, int lane) {
;     float v[16]; float s = 0.f;
;     const u32x4 w0 = *((const u32x4*)src + lane), w1 = *((const u32x4*)src + lane + 64);
;     unpack8bf(w0, v); unpack8bf(w1, v + 8);
; #pragma unroll
;     for (int e = 0; e < 16; ++e) s += v[e] * v[e];
;     const float rstd = 1.0f / sqrtf(wave_sum(s) * (1.f / DM) + NORM_EPS);
; #pragma unroll
;     for (int h = 0; h < 2; ++h) { const float* g = gain + h * 512 + lane * 8; const f32x4 g0 = *(const f32x4*)g, g1 = *(const f32x4*)(g + 4);
;         float o[8];
; #pragma unroll
;         for (int e = 0; e < 4; ++e) { o[e] = v[h * 8 + e] * rstd * g0[e]; o[4 + e] = v[h * 8 + 4 + e] * rstd * g1[e]; }
;         if (ob) { u32x4 w; w.x = pkbf(o[0], o[1]); w.y = pkbf(o[2], o[3]); w.z = pkbf(o[4], o[5]); w.w = pkbf(o[6], o[7]); *((u32x4*)ob + lane + 64 * h) = w; }
;         else { const f32x4 a = {o[0], o[1], o[2], o[3]}, b = {o[4], o[5], o[6], o[7]}; *(f32x4*)(of + h * 512 + lane * 8) = a; *(f32x4*)(of + h * 512 + lane * 8 + 4) = b; } }
; }
; __global__ void __launch_bounds__(512, 2) mega_fwd(const Args a) {
;     ...
;     for (int m = gw; m < T; m += NGW) norm_row_bf(D1 + (size_t)m * DM, p.in[29], nullptr, H + (size_t)m * DM, lane);
.LBB0_1499:
	s_or_b64 exec, exec, s[0:1]
	v_readlane_b32 s0, v237, 63
	v_readlane_b32 s1, v236, 0
	s_and_b64 vcc, exec, s[0:1]
	s_waitcnt lgkmcnt(0)
	s_barrier
	s_cbranch_vccnz .LBB0_1502
	v_mbcnt_hi_u32_b32 v0, -1, v210
	v_and_b32_e32 v1, 64, v0
	v_add_u32_e32 v1, 64, v1
	v_xor_b32_e32 v2, 1, v0
	v_cmp_lt_i32_e32 vcc, v2, v1
	s_ashr_i32 s35, s34, 31
	s_lshl_b64 s[0:1], s[34:35], 11
	v_cndmask_b32_e32 v2, v0, v2, vcc
	v_lshlrev_b32_e32 v6, 2, v2
	v_xor_b32_e32 v2, 2, v0
	v_cmp_lt_i32_e32 vcc, v2, v1
	v_mov_b32_e32 v129, 0
	s_add_u32 s0, s50, s0
	v_cndmask_b32_e32 v2, v0, v2, vcc
	v_lshlrev_b32_e32 v7, 2, v2
	v_xor_b32_e32 v2, 4, v0
	v_cmp_lt_i32_e32 vcc, v2, v1
	v_mov_b32_e32 v165, v129
	s_addc_u32 s1, s51, s1
	v_cndmask_b32_e32 v2, v0, v2, vcc
	v_lshlrev_b32_e32 v8, 2, v2
	v_xor_b32_e32 v2, 8, v0
	v_cmp_lt_i32_e32 vcc, v2, v1
	s_ashr_i32 s89, s88, 31
	s_lshl_b64 s[2:3], s[88:89], 11
	v_cndmask_b32_e32 v2, v0, v2, vcc
	v_lshlrev_b32_e32 v9, 2, v2
	v_xor_b32_e32 v2, 16, v0
	v_cmp_lt_i32_e32 vcc, v2, v1
	v_mov_b32_e32 v12, 0x358637bd
	s_mov_b32 s6, 0xf800000
	v_cndmask_b32_e32 v2, v0, v2, vcc
	v_lshlrev_b32_e32 v10, 2, v2
	v_xor_b32_e32 v2, 32, v0
	v_cmp_lt_i32_e32 vcc, v2, v1
	v_mov_b32_e32 v13, 0x260
	s_nop 0
	v_cndmask_b32_e32 v0, v0, v2, vcc
	v_lshl_add_u64 v[2:3], s[0:1], 0, v[164:165]
	s_mov_b64 s[0:1], 0x3000000
	v_lshl_add_u64 v[2:3], v[2:3], 0, s[0:1]
	s_lshl_b64 s[0:1], s[34:35], 12
	s_add_u32 s0, s48, s0
	s_addc_u32 s1, s49, s1
	v_lshlrev_b32_e32 v11, 2, v0
	v_lshl_add_u64 v[0:1], s[46:47], 0, v[128:129]
	v_lshl_add_u64 v[4:5], s[0:1], 0, v[128:129]
	s_lshl_b64 s[4:5], s[88:89], 12
	global_load_dwordx4 v[192:195], v[0:1], off offset:2048
	global_load_dwordx4 v[196:199], v[0:1], off offset:2064
	s_waitcnt vmcnt(0)
.LBB0_1501:
	global_load_dwordx4 v[14:17], v[2:3], off
	global_load_dwordx4 v[18:21], v[2:3], off offset:1024
	global_load_dwordx4 v[22:25], v[0:1], off offset:16
	global_load_dwordx4 v[26:29], v[0:1], off
	s_add_i32 s34, s34, s88
	v_lshl_add_u64 v[2:3], v[2:3], 0, s[2:3]
	s_cmp_gt_i32 s34, 0xbfff
	s_waitcnt vmcnt(3)
	v_lshlrev_b32_e32 v34, 16, v14
	v_and_b32_e32 v35, 0xffff0000, v14
	v_lshlrev_b32_e32 v14, 16, v15
	v_and_b32_e32 v15, 0xffff0000, v15
	v_pk_mul_f32 v[44:45], v[34:35], v[34:35]
	v_pk_mul_f32 v[46:47], v[14:15], v[14:15]
	v_add_f32_e32 v44, v44, v45
	v_lshlrev_b32_e32 v32, 16, v16
	v_and_b32_e32 v33, 0xffff0000, v16
	v_add_f32_e32 v44, v46, v44
	s_waitcnt vmcnt(2)
	v_and_b32_e32 v30, 0xffff0000, v21
	v_lshlrev_b32_e32 v31, 16, v21
	v_lshlrev_b32_e32 v36, 16, v20
	v_and_b32_e32 v37, 0xffff0000, v20
	v_pk_mul_f32 v[20:21], v[32:33], v[32:33]
	v_add_f32_e32 v44, v47, v44
	v_lshlrev_b32_e32 v16, 16, v17
	v_and_b32_e32 v17, 0xffff0000, v17
	v_add_f32_e32 v20, v20, v44
	v_pk_mul_f32 v[42:43], v[16:17], v[16:17]
	v_add_f32_e32 v20, v21, v20
	v_lshlrev_b32_e32 v38, 16, v18
	v_and_b32_e32 v39, 0xffff0000, v18
	v_add_f32_e32 v20, v42, v20
	v_pk_mul_f32 v[50:51], v[38:39], v[38:39]
	v_add_f32_e32 v20, v43, v20
	v_lshlrev_b32_e32 v40, 16, v19
	v_and_b32_e32 v41, 0xffff0000, v19
	v_add_f32_e32 v20, v50, v20
	v_pk_mul_f32 v[52:53], v[40:41], v[40:41]
	v_add_f32_e32 v20, v51, v20
	v_add_f32_e32 v20, v52, v20
	v_pk_mul_f32 v[48:49], v[36:37], v[36:37]
	v_add_f32_e32 v20, v53, v20
	v_add_f32_e32 v20, v48, v20
	v_pk_mul_f32 v[18:19], v[30:31], v[30:31]
	v_add_f32_e32 v20, v49, v20
	v_add_f32_e32 v19, v19, v20
	v_add_f32_e32 v18, v18, v19
	s_nop 1
	v_add_f32_dpp v18, v18, v18 quad_perm:[1,0,3,2] row_mask:0xf bank_mask:0xf bound_ctrl:1
	s_nop 1
	v_add_f32_dpp v18, v18, v18 quad_perm:[2,3,0,1] row_mask:0xf bank_mask:0xf bound_ctrl:1
	s_nop 1
	v_add_f32_dpp v18, v18, v18 row_half_mirror row_mask:0xf bank_mask:0xf bound_ctrl:1
	s_nop 1
	v_add_f32_dpp v18, v18, v18 row_mirror row_mask:0xf bank_mask:0xf bound_ctrl:1
	s_nop 0
	v_readlane_b32 s98, v18, 0
	v_readlane_b32 s99, v18, 16
	v_readlane_b32 s100, v18, 32
	v_readlane_b32 s101, v18, 48
	v_mov_b32_e32 v18, s98
	v_add_f32_e32 v18, s99, v18
	v_mov_b32_e32 v19, s100
	v_add_f32_e32 v19, s101, v19
	v_add_f32_e32 v18, v18, v19
	v_fmamk_f32 v18, v18, 0x3a800000, v12
	v_mul_f32_e32 v19, 0x4f800000, v18
	v_cmp_gt_f32_e32 vcc, s6, v18
	s_nop 1
	v_cndmask_b32_e32 v18, v18, v19, vcc
	v_sqrt_f32_e32 v19, v18
	s_nop 0
	v_add_u32_e32 v20, -1, v19
	v_add_u32_e32 v21, 1, v19
	v_fma_f32 v42, -v20, v19, v18
	v_fma_f32 v43, -v21, v19, v18
	v_cmp_ge_f32_e64 s[0:1], 0, v42
	s_nop 1
	v_cndmask_b32_e64 v19, v19, v20, s[0:1]
	v_cmp_lt_f32_e64 s[0:1], 0, v43
	s_nop 1
	v_cndmask_b32_e64 v19, v19, v21, s[0:1]
	v_mul_f32_e32 v20, 0x37800000, v19
	v_cndmask_b32_e32 v19, v19, v20, vcc
	v_cmp_class_f32_e32 vcc, v18, v13
	s_nop 1
	v_cndmask_b32_e32 v18, v19, v18, vcc
	v_div_scale_f32 v19, s[0:1], v18, v18, 1.0
	v_rcp_f32_e32 v21, v19
	v_div_scale_f32 v20, vcc, 1.0, v18, 1.0
	v_fma_f32 v42, -v19, v21, 1.0
	v_fmac_f32_e32 v21, v42, v21
	v_mul_f32_e32 v42, v20, v21
	v_fma_f32 v43, -v19, v42, v20
	v_fmac_f32_e32 v42, v43, v21
	v_fma_f32 v19, -v19, v42, v20
	v_div_fmas_f32 v19, v19, v21, v42
	v_div_fixup_f32 v42, v19, v18, 1.0
	v_pk_mul_f32 v[18:19], v[42:43], v[34:35] op_sel_hi:[0,1]
	v_pk_mul_f32 v[14:15], v[42:43], v[14:15] op_sel_hi:[0,1]
	v_pk_mul_f32 v[32:33], v[42:43], v[32:33] op_sel_hi:[0,1]
	v_pk_mul_f32 v[20:21], v[42:43], v[16:17] op_sel_hi:[0,1]
	s_waitcnt vmcnt(0)
	v_pk_mul_f32 v[16:17], v[28:29], v[14:15]
	v_pk_mul_f32 v[14:15], v[26:27], v[18:19]
	v_pk_mul_f32 v[20:21], v[24:25], v[20:21]
	v_pk_mul_f32 v[18:19], v[22:23], v[32:33]
	global_store_dwordx4 v[4:5], v[14:17], off nt
	global_store_dwordx4 v[4:5], v[18:21], off offset:16 nt
	s_nop 1
	v_mov_b64_e32 v[14:15], v[192:193]
	v_mov_b64_e32 v[16:17], v[194:195]
	s_nop 0
	s_nop 1
	v_mov_b64_e32 v[18:19], v[196:197]
	v_mov_b64_e32 v[20:21], v[198:199]
	v_pk_mul_f32 v[26:27], v[42:43], v[40:41] op_sel_hi:[0,1]
	v_pk_mul_f32 v[28:29], v[42:43], v[38:39] op_sel_hi:[0,1]
	v_pk_mul_f32 v[22:23], v[42:43], v[36:37] op_sel_hi:[0,1]
	v_pk_mul_f32 v[24:25], v[42:43], v[30:31] op_sel_hi:[0,1]
	s_nop 0
	v_pk_mul_f32 v[14:15], v[14:15], v[28:29]
	v_pk_mul_f32 v[16:17], v[16:17], v[26:27]
	s_nop 0
	v_pk_mul_f32 v[18:19], v[18:19], v[22:23]
	v_pk_mul_f32 v[20:21], v[20:21], v[24:25] op_sel:[0,1] op_sel_hi:[1,0]
	global_store_dwordx4 v[4:5], v[14:17], off offset:2048 nt
	global_store_dwordx4 v[4:5], v[18:21], off offset:2064 nt
	v_lshl_add_u64 v[4:5], v[4:5], 0, s[4:5]
	s_cbranch_scc0 .LBB0_1501
